# attention K/V tile loads: saddr form (uniform SGPR tile base + per-lane 32-bit offsets), 5 64-bit VALU adds per tile removed
# speedup vs baseline: 1.0133x; 1.0013x over previous
; __device__ __forceinline__ int my_tid() { int t = threadIdx.x; asm volatile("" : "+v"(t)); return t; }
; #define ATT_LOAD(tile) do { _Pragma("unroll") for (int i = 0; i < 2; ++i) { kr[i] = *(const u32x4*)(kg + (size_t)(64 * (tile) + 32 * i) * PP); vr[i] = *(const u32x4*)(vg + (size_t)(64 * (tile) + 32 * i) * PP); } } while (0)
; #define ATT_STORE(buf) do { LAS char* nb_ = lds + (buf) * ABUF; _Pragma("unroll") for (int i = 0; i < 2; ++i) { *(LAS u32x4*)(nb_ + soff + 32 * i * APIT) = kr[i]; *(LAS u32x4*)(nb_ + ATILE + soff + 32 * i * APIT) = vr[i]; } } while (0)
; __device__ __forceinline__ void attn_item(LAS char* lds, bf16_t* proj, int bl, int h, int qb, float lam, float oscale, const float* gdh, float smax) {
;     const int tid = my_tid(), lane = tid & 63, wid = __builtin_amdgcn_readfirstlane(tid >> 6), g = lane >> 4, fr = lane & 15;
;     const size_t rowbase = (size_t)bl * SEQ; const int q0 = qb * 128, qpos = q0 + 16 * wid + fr;
;     bf16_t* qp = proj + SEC(C_AQ) + (rowbase + qpos) * PP + h * 128;
;     bf16x8 qf[2][2];
; #pragma unroll
;     for (int c = 0; c < 2; ++c)
; #pragma unroll
;         for (int ks = 0; ks < 2; ++ks) qf[c][ks] = *(const bf16x8*)(qp + c * 64 + 32 * ks + 8 * g);
;     f32x4 O[2][8], Oe[2];
; #pragma unroll
;     for (int c = 0; c < 2; ++c) { Oe[c] = (f32x4){0.f, 0.f, 0.f, 0.f};
; #pragma unroll
;         for (int nb = 0; nb < 8; ++nb) O[c][nb] = (f32x4){0.f, 0.f, 0.f, 0.f}; }
;     const f32x4 negM = (f32x4){-smax, -smax, -smax, -smax};
;     const short one16 = (fr == 0) ? (short)0x3F80 : (short)0;
;     const bf16x8 onesf = (bf16x8){one16, one16, one16, one16, one16, one16, one16, one16};
;     const int NT = 2 * (qb + 1);
;     const int sr0 = tid >> 4, sc = tid & 15;
;     const bf16_t* kg = proj + SEC(C_AK) + (rowbase + sr0) * PP + h * 128 + sc * 8;
;     const bf16_t* vg = proj + SEC(C_AV) + (rowbase + sr0) * PP + h * 128 + sc * 8;
;     const int soff = sr0 * APIT + sc * 16;
;     u32x4 kr[2], vr[2];
;     ...
;     ATT_LOAD(0); ATT_STORE(0);
;     __syncthreads();
;     const int qmaxw = q0 + 16 * wid + 15;
;     int t = 0;
;     for (; t < NT - 2; ++t) {
;         ATT_LOAD(t + 1);
.LBB0_241:
	s_and_b32 s0, s40, 7
	s_lshl_b32 s44, s0, 8
	s_bfe_u32 s0, s41, 0x50003
	s_and_b32 s42, s41, 7
	s_and_b32 s1, s41, 0x100
	s_xor_b32 s4, s0, 31
	s_cmp_eq_u32 s1, 0
	v_mov_b32_e32 v14, v194
	s_cselect_b32 s45, s0, s4
	s_lshl_b32 s46, s45, 7
	v_readfirstlane_b32 s4, v14
	s_ashr_i32 s4, s4, 2
	s_and_b32 s43, s4, -16
	s_ashr_i32 s36, s41, 8
	v_and_b32_e32 v176, 15, v14
	s_add_i32 s43, s43, s46
	s_ashr_i32 s37, s36, 31
	v_or_b32_e32 v164, s43, v176
	s_lshl_b64 s[0:1], s[36:37], 12
	v_ashrrev_i32_e32 v165, 31, v164
	v_lshl_add_u64 v[162:163], s[0:1], 0, v[164:165]
	v_readlane_b32 s4, v252, 28
	v_lshlrev_b64 v[6:7], 11, v[162:163]
	v_readlane_b32 s5, v252, 29
	s_lshl_b32 s84, s42, 8
	v_lshlrev_b32_e32 v0, 4, v176
	v_lshl_add_u64 v[6:7], s[4:5], 0, v[6:7]
	v_lshl_add_u64 v[8:9], v[6:7], 0, s[84:85]
	v_ashrrev_i32_e32 v6, 4, v14
	v_ashrrev_i32_e32 v7, 31, v6
	v_lshl_add_u64 v[10:11], s[0:1], 0, v[6:7]
	v_readlane_b32 s0, v252, 30
	v_lshlrev_b64 v[10:11], 11, v[10:11]
	v_readlane_b32 s1, v252, 31
	v_and_b32_e32 v166, 48, v14
	v_mov_b32_e32 v167, v1
	v_lshl_add_u64 v[12:13], s[0:1], 0, v[10:11]
	v_readlane_b32 s0, v252, 32
	v_readlane_b32 s1, v252, 33
	v_lshl_add_u64 v[12:13], v[12:13], 0, s[84:85]
	v_lshl_add_u64 v[12:13], v[12:13], 0, v[0:1]
	v_lshl_add_u64 v[10:11], s[0:1], 0, v[10:11]
	v_lshl_add_u64 v[10:11], v[10:11], 0, s[84:85]
	s_mov_b32 s0, 0x10000
	v_lshl_add_u64 v[10:11], v[10:11], 0, v[0:1]
	global_load_dwordx4 v[118:121], v[12:13], off
	global_load_dwordx4 v[114:117], v[10:11], off
	v_add_co_u32_e32 v12, vcc, s0, v12
	v_lshl_add_u64 v[8:9], v[8:9], 0, v[166:167]
	s_nop 0
	v_addc_co_u32_e32 v13, vcc, 0, v13, vcc
	v_add_co_u32_e32 v10, vcc, s0, v10
	s_movk_i32 s0, 0x120
	s_nop 0
	v_addc_co_u32_e32 v11, vcc, 0, v11, vcc
	global_load_dwordx4 v[122:125], v[12:13], off
	global_load_dwordx4 v[126:129], v[10:11], off
	global_load_dwordx4 v[34:37], v[8:9], off
	global_load_dwordx4 v[38:41], v[8:9], off offset:64
	global_load_dwordx4 v[42:45], v[8:9], off offset:128
	global_load_dwordx4 v[50:53], v[8:9], off offset:192
	v_cmp_eq_u32_e32 vcc, 0, v176
	v_mov_b32_e32 v11, 0x3f80
	v_and_b32_e32 v8, 63, v14
	v_cndmask_b32_e32 v11, 0, v11, vcc
	v_mul_lo_u32 v12, v6, s0
	s_mov_b32 s0, 0x5040100
	v_bfe_u32 v9, v14, 2, 4
	v_lshlrev_b32_e32 v10, 3, v14
	v_or_b32_e32 v8, 48, v8
	v_perm_b32 v74, v11, v11, s0
	v_mul_u32_u24_e32 v167, 0x120, v176
	v_and_b32_e32 v165, 12, v9
	v_mul_u32_u24_e32 v177, 0x120, v9
	v_and_b32_e32 v178, 24, v10
	v_add3_u32 v179, v12, v0, 0
	v_mul_u32_u24_e32 v180, 0x120, v8
	v_mov_b32_e32 v75, v74
	v_mov_b32_e32 v76, v74
	v_mov_b32_e32 v77, v74
	s_cmp_lg_u32 s45, 0
	v_lshlrev_b64 v[170:171], 11, v[6:7]
	s_waitcnt vmcnt(7)
	ds_write_b128 v179, v[118:121]
	s_waitcnt vmcnt(6)
	ds_write_b128 v179, v[114:117] offset:18432
	s_waitcnt vmcnt(5)
	ds_write_b128 v179, v[122:125] offset:9216
	s_waitcnt vmcnt(4)
	ds_write_b128 v179, v[126:129] offset:27648
	s_waitcnt lgkmcnt(0)
	s_barrier
	s_cbranch_scc0 .LBB0_259
	s_lshl_b64 s[38:39], s[36:37], 23
	v_lshlrev_b64 v[168:169], 11, v[6:7]
	v_lshl_add_u64 v[6:7], s[38:39], 0, v[168:169]
	v_or_b32_e32 v6, s44, v6
	v_readlane_b32 s0, v254, 29
	v_lshl_add_u64 v[6:7], v[6:7], 0, v[0:1]
	v_readlane_b32 s1, v254, 30
	v_mov_b32_e32 v86, 0
	s_mov_b32 s47, 0
	v_lshl_add_u64 v[172:173], s[0:1], 0, v[6:7]
	s_mov_b32 s48, 1
	v_mov_b32_e32 v87, v86
	v_mov_b32_e32 v88, v86
	v_mov_b32_e32 v89, v86
	v_mov_b32_e32 v66, v86
	v_mov_b32_e32 v67, v86
	v_mov_b32_e32 v68, v86
	v_mov_b32_e32 v69, v86
	v_mov_b32_e32 v10, v86
	v_mov_b32_e32 v11, v86
	v_mov_b32_e32 v12, v86
	v_mov_b32_e32 v13, v86
	v_mov_b32_e32 v6, v86
	v_mov_b32_e32 v7, v86
	v_mov_b32_e32 v8, v86
	v_mov_b32_e32 v9, v86
	v_mov_b32_e32 v14, v86
	v_mov_b32_e32 v15, v86
	v_mov_b32_e32 v16, v86
	v_mov_b32_e32 v17, v86
	v_mov_b32_e32 v18, v86
	v_mov_b32_e32 v19, v86
	v_mov_b32_e32 v20, v86
	v_mov_b32_e32 v21, v86
	v_mov_b32_e32 v22, v86
	v_mov_b32_e32 v23, v86
	v_mov_b32_e32 v24, v86
	v_mov_b32_e32 v25, v86
	v_mov_b32_e32 v26, v86
	v_mov_b32_e32 v27, v86
	v_mov_b32_e32 v28, v86
	v_mov_b32_e32 v29, v86
	v_mov_b32_e32 v30, v86
	v_mov_b32_e32 v31, v86
	v_mov_b32_e32 v32, v86
	v_mov_b32_e32 v33, v86
	v_mov_b32_e32 v46, v86
	v_mov_b32_e32 v47, v86
	v_mov_b32_e32 v48, v86
	v_mov_b32_e32 v49, v86
	v_mov_b32_e32 v54, v86
	v_mov_b32_e32 v55, v86
	v_mov_b32_e32 v56, v86
	v_mov_b32_e32 v57, v86
	v_mov_b32_e32 v58, v86
	v_mov_b32_e32 v59, v86
	v_mov_b32_e32 v60, v86
	v_mov_b32_e32 v61, v86
	v_mov_b32_e32 v62, v86
	v_mov_b32_e32 v63, v86
	v_mov_b32_e32 v64, v86
	v_mov_b32_e32 v65, v86
	v_mov_b32_e32 v70, v86
	v_mov_b32_e32 v71, v86
	v_mov_b32_e32 v72, v86
	v_mov_b32_e32 v73, v86
	v_mov_b32_e32 v78, v86
	v_mov_b32_e32 v79, v86
	v_mov_b32_e32 v80, v86
	v_mov_b32_e32 v81, v86
	v_mov_b32_e32 v90, v86
	v_mov_b32_e32 v91, v86
	v_mov_b32_e32 v92, v86
	v_mov_b32_e32 v93, v86
	v_mov_b32_e32 v94, v86
	v_mov_b32_e32 v95, v86
	v_mov_b32_e32 v96, v86
	v_mov_b32_e32 v97, v86
	v_mov_b32_e32 v82, v86
	v_mov_b32_e32 v83, v86
	v_mov_b32_e32 v84, v86
	v_mov_b32_e32 v85, v86
	v_add_u32_e32 v230, v166, v167
	v_add_u32_e32 v231, v177, v178
	v_readfirstlane_b32 s4, v172
	v_readfirstlane_b32 s5, v173
	s_nop 1
	v_subrev_u32_e32 v172, s4, v172
	s_add_u32 s4, s4, 0xfdff0000
	s_addc_u32 s5, s5, -1
	v_add_u32_e32 v173, 0x10000, v172
	v_add_u32_e32 v240, 0x1fe0000, v172
	v_add_u32_e32 v241, 0x1ff0000, v172
	s_mov_b32 s49, 0
	s_mov_b32 s50, 0x9000
	v_add_u32_e32 v181, s49, v230
	ds_read_b128 v[206:209], v181
	ds_read_b128 v[210:213], v181 offset:64
	ds_read_b128 v[214:217], v181 offset:4608
	ds_read_b128 v[218:221], v181 offset:4672
	ds_read_b128 v[222:225], v181 offset:9216
	global_load_dwordx4 v[146:149], v172, s[4:5]
	global_load_dwordx4 v[150:153], v173, s[4:5]
	s_add_u32 s4, s4, 0x20000
	s_addc_u32 s5, s5, 0
	s_waitcnt vmcnt(2)
; #define LAS __attribute__((address_space(3)))
; __device__ __forceinline__ f32x4 mfma16(bf16x8 a, bf16x8 b, f32x4 c) { return __builtin_amdgcn_mfma_f32_16x16x32_bf16(a, b, c, 0, 0, 0); }
; #define BAR_LDS() do { asm volatile("s_waitcnt lgkmcnt(0)" ::: "memory"); __builtin_amdgcn_s_barrier(); asm volatile("" ::: "memory"); } while (0)
; #define ATT_LOAD(tile) do { _Pragma("unroll") for (int i = 0; i < 2; ++i) { kr[i] = *(const u32x4*)(kg + (size_t)(64 * (tile) + 32 * i) * PP); vr[i] = *(const u32x4*)(vg + (size_t)(64 * (tile) + 32 * i) * PP); } } while (0)
; __device__ __forceinline__ void attn_step_fast(const LAS char* Kb, const LAS char* Vb, int lane, const bf16x8 (&qf)[2][2], const f32x4 negM, const bf16x8 onesf, f32x4 (&O)[2][8], f32x4 (&Oe)[2]) {
;     f32x4 s0[4], s1[4];
;     bf16x8 p0[2], p1[2];
;     {
;         bf16x8 kf[2][4][2];
; #pragma unroll
;         for (int c = 0; c < 2; ++c)
; #pragma unroll
;             for (int kb = 0; kb < 4; ++kb)
; #pragma unroll
;                 for (int ks = 0; ks < 2; ++ks) kf[c][kb][ks] = rowfrag(Kb, APIT, 16 * kb, c * 64 + 32 * ks, lane);
;         __builtin_amdgcn_sched_barrier(0);
; #pragma unroll
;         for (int kb = 0; kb < 4; ++kb) s0[kb] = mfma16(kf[0][kb][0], qf[0][0], negM);
; #pragma unroll
;         for (int kb = 0; kb < 4; ++kb) s0[kb] = mfma16(kf[0][kb][1], qf[0][1], s0[kb]);
;         __builtin_amdgcn_sched_barrier(0);
; #pragma unroll
;         for (int kb = 0; kb < 4; ++kb) s1[kb] = mfma16(kf[1][kb][0], qf[1][0], negM);
; #pragma unroll
;         for (int kb = 0; kb < 4; ++kb) s1[kb] = mfma16(kf[1][kb][1], qf[1][1], s1[kb]);
;     }
;     ...
;     ATT_EXPPACK(s0, p0);
; #pragma unroll
;     for (int i = 0; i < 8; ++i) { __builtin_amdgcn_sched_group_barrier(0x008, 1, 0); __builtin_amdgcn_sched_group_barrier(0x002, 3, 0); }
;     __builtin_amdgcn_sched_barrier(0);
; __device__ __forceinline__ void attn_item(LAS char* lds, bf16_t* proj, int bl, int h, int qb, float lam, float oscale, const float* gdh, float smax) {
;     ...
;     for (; t < NT - 2; ++t) {
;         ATT_LOAD(t + 1);
;         const LAS char* Kb = lds + (t & 1) * ABUF;
;     ...
;         attn_step_fast(Kb, Kb + ATILE, lane, qf, negM, onesf, O, Oe);
;     ...
;         { bf16x8 pq[2][2]; attn_qkexp(Kb, 64 * t, q0, wid, lane, g, qpos, qf, negM, pq); attn_pv(Kb + ATILE, lane, pq, onesf, O, Oe); }
;     ...
;         ATT_STORE((t + 1) & 1);
;         BAR_LDS();
	s_waitcnt lgkmcnt(4)
	v_mfma_f32_16x16x32_bf16 v[98:101], v[206:209], v[34:37], v[2:5]
	ds_read_b128 v[206:209], v181 offset:9280
	s_waitcnt lgkmcnt(4)
	v_mfma_f32_16x16x32_bf16 v[98:101], v[210:213], v[38:41], v[98:101]
	ds_read_b128 v[210:213], v181 offset:13824
	s_waitcnt lgkmcnt(4)
	v_mfma_f32_16x16x32_bf16 v[102:105], v[214:217], v[34:37], v[2:5]
	ds_read_b128 v[214:217], v181 offset:13888
	s_waitcnt lgkmcnt(4)
	v_mfma_f32_16x16x32_bf16 v[102:105], v[218:221], v[38:41], v[102:105]
	ds_read_b128 v[218:221], v181 offset:128
	s_waitcnt lgkmcnt(4)
	v_mfma_f32_16x16x32_bf16 v[106:109], v[222:225], v[34:37], v[2:5]
	ds_read_b128 v[222:225], v181 offset:192
	s_waitcnt lgkmcnt(4)
	v_mfma_f32_16x16x32_bf16 v[106:109], v[206:209], v[38:41], v[106:109]
	ds_read_b128 v[206:209], v181 offset:4736
	s_waitcnt lgkmcnt(4)
	v_mfma_f32_16x16x32_bf16 v[110:113], v[210:213], v[34:37], v[2:5]
	ds_read_b128 v[210:213], v181 offset:4800
	s_waitcnt lgkmcnt(4)
	v_mfma_f32_16x16x32_bf16 v[110:113], v[214:217], v[38:41], v[110:113]
	ds_read_b128 v[214:217], v181 offset:9344
	s_waitcnt lgkmcnt(4)
	v_mfma_f32_16x16x32_bf16 v[114:117], v[218:221], v[42:45], v[2:5]
	ds_read_b128 v[218:221], v181 offset:9408
	s_waitcnt lgkmcnt(4)
	v_mfma_f32_16x16x32_bf16 v[114:117], v[222:225], v[50:53], v[114:117]
	ds_read_b128 v[222:225], v181 offset:13952
	s_waitcnt lgkmcnt(4)
	v_mfma_f32_16x16x32_bf16 v[118:121], v[206:209], v[42:45], v[2:5]
	ds_read_b128 v[206:209], v181 offset:14016
	s_waitcnt lgkmcnt(4)
	v_mfma_f32_16x16x32_bf16 v[118:121], v[210:213], v[50:53], v[118:121]
	s_waitcnt lgkmcnt(3)
	v_mfma_f32_16x16x32_bf16 v[122:125], v[214:217], v[42:45], v[2:5]
	s_waitcnt lgkmcnt(2)
	v_mfma_f32_16x16x32_bf16 v[122:125], v[218:221], v[50:53], v[122:125]
	s_waitcnt lgkmcnt(1)
	v_mfma_f32_16x16x32_bf16 v[126:129], v[222:225], v[42:45], v[2:5]
	s_waitcnt lgkmcnt(0)
	v_mfma_f32_16x16x32_bf16 v[126:129], v[206:209], v[50:53], v[126:129]
	v_add_u32_e32 v238, s50, v179
	s_nop 7
	v_exp_f32_e32 v98, v98
	v_exp_f32_e32 v99, v99
	v_exp_f32_e32 v100, v100
	v_exp_f32_e32 v101, v101
	v_exp_f32_e32 v114, v114
	v_exp_f32_e32 v115, v115
	v_exp_f32_e32 v116, v116
	v_exp_f32_e32 v117, v117
	v_exp_f32_e32 v102, v102
	v_exp_f32_e32 v103, v103
	v_exp_f32_e32 v104, v104
	v_exp_f32_e32 v105, v105
	v_exp_f32_e32 v118, v118
	v_exp_f32_e32 v119, v119
	v_exp_f32_e32 v120, v120
	v_exp_f32_e32 v121, v121
	v_exp_f32_e32 v106, v106
	v_exp_f32_e32 v107, v107
	v_exp_f32_e32 v108, v108
	v_exp_f32_e32 v109, v109
	v_exp_f32_e32 v122, v122
	v_exp_f32_e32 v123, v123
	v_exp_f32_e32 v124, v124
	v_exp_f32_e32 v125, v125
	v_exp_f32_e32 v110, v110
	v_exp_f32_e32 v111, v111
	v_exp_f32_e32 v112, v112
	v_exp_f32_e32 v113, v113
	v_exp_f32_e32 v126, v126
	v_exp_f32_e32 v127, v127
	v_exp_f32_e32 v128, v128
	v_exp_f32_e32 v129, v129
	v_cvt_pk_bf16_f32 v130, v98, v99
	v_cvt_pk_bf16_f32 v131, v100, v101
	v_cvt_pk_bf16_f32 v132, v102, v103
	v_cvt_pk_bf16_f32 v133, v104, v105
	v_cvt_pk_bf16_f32 v138, v114, v115
	v_cvt_pk_bf16_f32 v139, v116, v117
	v_cvt_pk_bf16_f32 v140, v118, v119
	v_cvt_pk_bf16_f32 v141, v120, v121
	s_waitcnt vmcnt(1)
	ds_write_b128 v238, v[146:149]
	s_waitcnt vmcnt(0)
	ds_write_b128 v238, v[150:153] offset:9216
	s_waitcnt lgkmcnt(0)
	s_barrier
	s_lshl_b32 s47, s45, 1
	s_add_i32 s47, s47, -1
	s_mov_b32 s49, 0x9000
	s_mov_b32 s50, 0
.Lmy_attn_loop:
	v_add_u32_e32 v181, s49, v230
	v_add_u32_e32 v205, s50, v231
	ds_read_b128 v[206:209], v181
	ds_read_b128 v[210:213], v181 offset:64
	ds_read_b128 v[214:217], v181 offset:4608
	ds_read_b128 v[218:221], v181 offset:4672
	ds_read_b128 v[222:225], v181 offset:9216
	global_load_dwordx4 v[146:149], v172, s[4:5]
	global_load_dwordx4 v[150:153], v173, s[4:5]
	global_load_dwordx4 v[154:157], v240, s[4:5]
	global_load_dwordx4 v[158:161], v241, s[4:5]
	s_add_u32 s4, s4, 0x20000
	s_addc_u32 s5, s5, 0
	v_cvt_pk_bf16_f32 v134, v106, v107
	v_cvt_pk_bf16_f32 v135, v108, v109
	v_cvt_pk_bf16_f32 v136, v110, v111
	v_cvt_pk_bf16_f32 v137, v112, v113
	v_cvt_pk_bf16_f32 v142, v122, v123
	v_cvt_pk_bf16_f32 v143, v124, v125
	v_cvt_pk_bf16_f32 v144, v126, v127
	v_cvt_pk_bf16_f32 v145, v128, v129
	s_waitcnt lgkmcnt(4)
	v_mfma_f32_16x16x32_bf16 v[98:101], v[206:209], v[34:37], v[2:5]
	ds_read_b128 v[206:209], v181 offset:9280
	s_waitcnt lgkmcnt(4)
	v_mfma_f32_16x16x32_bf16 v[98:101], v[210:213], v[38:41], v[98:101]
	ds_read_b128 v[210:213], v181 offset:13824
	s_waitcnt lgkmcnt(4)
	v_mfma_f32_16x16x32_bf16 v[102:105], v[214:217], v[34:37], v[2:5]
	ds_read_b128 v[214:217], v181 offset:13888
	s_waitcnt lgkmcnt(4)
	v_mfma_f32_16x16x32_bf16 v[102:105], v[218:221], v[38:41], v[102:105]
	ds_read_b128 v[218:221], v181 offset:128
	s_waitcnt lgkmcnt(4)
	v_mfma_f32_16x16x32_bf16 v[106:109], v[222:225], v[34:37], v[2:5]
	ds_read_b128 v[222:225], v181 offset:192
	s_waitcnt lgkmcnt(4)
	v_mfma_f32_16x16x32_bf16 v[106:109], v[206:209], v[38:41], v[106:109]
	ds_read_b128 v[206:209], v181 offset:4736
	s_waitcnt lgkmcnt(4)
	v_mfma_f32_16x16x32_bf16 v[110:113], v[210:213], v[34:37], v[2:5]
	ds_read_b128 v[210:213], v181 offset:4800
	s_waitcnt lgkmcnt(4)
	v_mfma_f32_16x16x32_bf16 v[110:113], v[214:217], v[38:41], v[110:113]
	ds_read_b128 v[214:217], v181 offset:9344
	s_waitcnt lgkmcnt(4)
	v_mfma_f32_16x16x32_bf16 v[114:117], v[218:221], v[42:45], v[2:5]
	ds_read_b128 v[218:221], v181 offset:9408
	s_waitcnt lgkmcnt(4)
	v_mfma_f32_16x16x32_bf16 v[114:117], v[222:225], v[50:53], v[114:117]
	ds_read_b128 v[222:225], v181 offset:13952
	s_waitcnt lgkmcnt(4)
	v_mfma_f32_16x16x32_bf16 v[118:121], v[206:209], v[42:45], v[2:5]
	ds_read_b128 v[206:209], v181 offset:14016
	ds_read_b64_tr_b16 v[182:183], v205 offset:18432
	ds_read_b64_tr_b16 v[184:185], v205 offset:23040
	s_waitcnt lgkmcnt(6)
; __device__ __forceinline__ f32x4 mfma16(bf16x8 a, bf16x8 b, f32x4 c) { return __builtin_amdgcn_mfma_f32_16x16x32_bf16(a, b, c, 0, 0, 0); }
; __device__ __forceinline__ void attn_step_fast(const LAS char* Kb, const LAS char* Vb, int lane, const bf16x8 (&qf)[2][2], const f32x4 negM, const bf16x8 onesf, f32x4 (&O)[2][8], f32x4 (&Oe)[2]) {
;     ...
;     ATT_EXPPACK(s0, p0);
; #pragma unroll
;     for (int i = 0; i < 8; ++i) { __builtin_amdgcn_sched_group_barrier(0x008, 1, 0); __builtin_amdgcn_sched_group_barrier(0x002, 3, 0); }
;     __builtin_amdgcn_sched_barrier(0);
;     bf16x8 va[8], vb[8];
; #pragma unroll
;     for (int nb = 0; nb < 8; ++nb) va[nb] = trfrag(Vb, APIT, 0, 16 * nb, lane);
; #pragma unroll
;     for (int nb = 0; nb < 8; ++nb) vb[nb] = trfrag(Vb, APIT, 32, 16 * nb, lane);
;     __builtin_amdgcn_sched_barrier(0);
;     Oe[0] = mfma16(onesf, p0[0], Oe[0]);
; #pragma unroll
;     for (int nb = 0; nb < 8; ++nb) O[0][nb] = mfma16(va[nb], p0[0], O[0][nb]);
;     Oe[0] = mfma16(onesf, p0[1], Oe[0]);
; #pragma unroll
;     for (int nb = 0; nb < 8; ++nb) O[0][nb] = mfma16(vb[nb], p0[1], O[0][nb]);
;     ATT_EXPPACK(s1, p1);
; #pragma unroll
;     for (int i = 0; i < 18; ++i) { __builtin_amdgcn_sched_group_barrier(0x008, 1, 0); __builtin_amdgcn_sched_group_barrier(0x002, 2, 0); }
;     __builtin_amdgcn_sched_barrier(0);
;     Oe[1] = mfma16(onesf, p1[0], Oe[1]);
; #pragma unroll
;     for (int nb = 0; nb < 8; ++nb) O[1][nb] = mfma16(va[nb], p1[0], O[1][nb]);
;     Oe[1] = mfma16(onesf, p1[1], Oe[1]);
; #pragma unroll
;     for (int nb = 0; nb < 8; ++nb) O[1][nb] = mfma16(vb[nb], p1[1], O[1][nb]);
	v_mfma_f32_16x16x32_bf16 v[118:121], v[210:213], v[50:53], v[118:121]
	ds_read_b64_tr_b16 v[186:187], v205 offset:18464
	ds_read_b64_tr_b16 v[188:189], v205 offset:23072
	s_waitcnt lgkmcnt(7)
	v_mfma_f32_16x16x32_bf16 v[122:125], v[214:217], v[42:45], v[2:5]
	ds_read_b64_tr_b16 v[190:191], v205 offset:18496
	ds_read_b64_tr_b16 v[192:193], v205 offset:23104
	s_waitcnt lgkmcnt(8)
	v_mfma_f32_16x16x32_bf16 v[122:125], v[218:221], v[50:53], v[122:125]
	ds_read_b64_tr_b16 v[226:227], v205 offset:18528
	ds_read_b64_tr_b16 v[228:229], v205 offset:23136
	s_waitcnt lgkmcnt(9)
	v_mfma_f32_16x16x32_bf16 v[126:129], v[222:225], v[42:45], v[2:5]
	ds_read_b64_tr_b16 v[244:245], v205 offset:18560
	ds_read_b64_tr_b16 v[246:247], v205 offset:23168
	s_waitcnt lgkmcnt(10)
	v_mfma_f32_16x16x32_bf16 v[126:129], v[206:209], v[50:53], v[126:129]
	ds_read_b64_tr_b16 v[248:249], v205 offset:18592
	ds_read_b64_tr_b16 v[250:251], v205 offset:23200
	v_add_u32_e32 v238, s50, v179
	v_add_u32_e32 v239, s49, v179
	v_mfma_f32_16x16x32_bf16 v[94:97], v[74:77], v[130:133], v[94:97]
	v_exp_f32_e32 v98, v98
	v_mfma_f32_16x16x32_bf16 v[90:93], v[74:77], v[138:141], v[90:93]
	v_exp_f32_e32 v99, v99
	s_waitcnt lgkmcnt(10)
	v_mfma_f32_16x16x32_bf16 v[82:85], v[182:185], v[130:133], v[82:85]
	v_exp_f32_e32 v100, v100
	v_mfma_f32_16x16x32_bf16 v[78:81], v[182:185], v[138:141], v[78:81]
	ds_read_b64_tr_b16 v[182:183], v205 offset:18624
	ds_read_b64_tr_b16 v[184:185], v205 offset:23232
	v_exp_f32_e32 v101, v101
	s_waitcnt lgkmcnt(10)
	v_mfma_f32_16x16x32_bf16 v[70:73], v[186:189], v[130:133], v[70:73]
	v_exp_f32_e32 v114, v114
	v_mfma_f32_16x16x32_bf16 v[62:65], v[186:189], v[138:141], v[62:65]
	ds_read_b64_tr_b16 v[186:187], v205 offset:18656
	ds_read_b64_tr_b16 v[188:189], v205 offset:23264
	v_exp_f32_e32 v115, v115
	s_waitcnt lgkmcnt(10)
	v_mfma_f32_16x16x32_bf16 v[58:61], v[190:193], v[130:133], v[58:61]
	v_exp_f32_e32 v116, v116
	v_mfma_f32_16x16x32_bf16 v[54:57], v[190:193], v[138:141], v[54:57]
	ds_read_b64_tr_b16 v[190:191], v205 offset:27648
	ds_read_b64_tr_b16 v[192:193], v205 offset:32256
	v_exp_f32_e32 v117, v117
	s_waitcnt lgkmcnt(10)
	v_mfma_f32_16x16x32_bf16 v[46:49], v[226:229], v[130:133], v[46:49]
	v_exp_f32_e32 v102, v102
	v_mfma_f32_16x16x32_bf16 v[30:33], v[226:229], v[138:141], v[30:33]
	ds_read_b64_tr_b16 v[226:227], v205 offset:27680
	ds_read_b64_tr_b16 v[228:229], v205 offset:32288
	v_exp_f32_e32 v103, v103
	s_waitcnt lgkmcnt(10)
	v_mfma_f32_16x16x32_bf16 v[26:29], v[244:247], v[130:133], v[26:29]
	v_exp_f32_e32 v104, v104
	v_mfma_f32_16x16x32_bf16 v[22:25], v[244:247], v[138:141], v[22:25]
	ds_read_b64_tr_b16 v[244:245], v205 offset:27712
	ds_read_b64_tr_b16 v[246:247], v205 offset:32320
	v_exp_f32_e32 v105, v105
	s_waitcnt lgkmcnt(10)
	v_mfma_f32_16x16x32_bf16 v[18:21], v[248:251], v[130:133], v[18:21]
	v_exp_f32_e32 v118, v118
	v_mfma_f32_16x16x32_bf16 v[14:17], v[248:251], v[138:141], v[14:17]
	ds_read_b64_tr_b16 v[248:249], v205 offset:27744
	ds_read_b64_tr_b16 v[250:251], v205 offset:32352
	v_exp_f32_e32 v119, v119
	s_waitcnt lgkmcnt(10)
	v_mfma_f32_16x16x32_bf16 v[6:9], v[182:185], v[130:133], v[6:9]
	v_exp_f32_e32 v120, v120
	v_mfma_f32_16x16x32_bf16 v[10:13], v[182:185], v[138:141], v[10:13]
	ds_read_b64_tr_b16 v[182:183], v205 offset:27776
	ds_read_b64_tr_b16 v[184:185], v205 offset:32384
	v_exp_f32_e32 v121, v121
	s_waitcnt lgkmcnt(10)
	v_mfma_f32_16x16x32_bf16 v[66:69], v[186:189], v[130:133], v[66:69]
	v_exp_f32_e32 v106, v106
	v_mfma_f32_16x16x32_bf16 v[86:89], v[186:189], v[138:141], v[86:89]
	ds_read_b64_tr_b16 v[186:187], v205 offset:27808
	ds_read_b64_tr_b16 v[188:189], v205 offset:32416
	v_exp_f32_e32 v107, v107
	v_mfma_f32_16x16x32_bf16 v[94:97], v[74:77], v[134:137], v[94:97]
	v_exp_f32_e32 v108, v108
	v_mfma_f32_16x16x32_bf16 v[90:93], v[74:77], v[142:145], v[90:93]
	v_exp_f32_e32 v109, v109
	s_waitcnt lgkmcnt(10)
	v_mfma_f32_16x16x32_bf16 v[82:85], v[190:193], v[134:137], v[82:85]
	v_exp_f32_e32 v122, v122
	v_mfma_f32_16x16x32_bf16 v[78:81], v[190:193], v[142:145], v[78:81]
	ds_read_b64_tr_b16 v[190:191], v205 offset:27840
	ds_read_b64_tr_b16 v[192:193], v205 offset:32448
	v_exp_f32_e32 v123, v123
	s_waitcnt lgkmcnt(10)
	v_mfma_f32_16x16x32_bf16 v[70:73], v[226:229], v[134:137], v[70:73]
	v_exp_f32_e32 v124, v124
	v_mfma_f32_16x16x32_bf16 v[62:65], v[226:229], v[142:145], v[62:65]
	ds_read_b64_tr_b16 v[226:227], v205 offset:27872
	ds_read_b64_tr_b16 v[228:229], v205 offset:32480
	v_exp_f32_e32 v125, v125
	s_waitcnt lgkmcnt(10)
	v_mfma_f32_16x16x32_bf16 v[58:61], v[244:247], v[134:137], v[58:61]
	v_exp_f32_e32 v110, v110
	v_mfma_f32_16x16x32_bf16 v[54:57], v[244:247], v[142:145], v[54:57]
	v_exp_f32_e32 v111, v111
	s_waitcnt lgkmcnt(8)
	v_mfma_f32_16x16x32_bf16 v[46:49], v[248:251], v[134:137], v[46:49]
	v_exp_f32_e32 v112, v112
	v_mfma_f32_16x16x32_bf16 v[30:33], v[248:251], v[142:145], v[30:33]
	v_exp_f32_e32 v113, v113
	s_waitcnt lgkmcnt(6)
	v_mfma_f32_16x16x32_bf16 v[26:29], v[182:185], v[134:137], v[26:29]
	v_exp_f32_e32 v126, v126
	s_waitcnt vmcnt(3)
	ds_write_b128 v238, v[146:149]
	v_mfma_f32_16x16x32_bf16 v[22:25], v[182:185], v[142:145], v[22:25]
	v_exp_f32_e32 v127, v127
	s_waitcnt lgkmcnt(5)
	v_mfma_f32_16x16x32_bf16 v[18:21], v[186:189], v[134:137], v[18:21]
	v_exp_f32_e32 v128, v128
	s_waitcnt vmcnt(2)
	ds_write_b128 v238, v[150:153] offset:9216
	v_mfma_f32_16x16x32_bf16 v[14:17], v[186:189], v[142:145], v[14:17]
	v_exp_f32_e32 v129, v129
	s_waitcnt lgkmcnt(4)
	v_mfma_f32_16x16x32_bf16 v[6:9], v[190:193], v[134:137], v[6:9]
	v_cvt_pk_bf16_f32 v130, v98, v99
	v_cvt_pk_bf16_f32 v131, v100, v101
	s_waitcnt vmcnt(1)
	ds_write_b128 v239, v[154:157] offset:18432
	v_mfma_f32_16x16x32_bf16 v[10:13], v[190:193], v[142:145], v[10:13]
	v_cvt_pk_bf16_f32 v132, v102, v103
	v_cvt_pk_bf16_f32 v133, v104, v105
	s_waitcnt lgkmcnt(3)
	v_mfma_f32_16x16x32_bf16 v[66:69], v[226:229], v[134:137], v[66:69]
	v_cvt_pk_bf16_f32 v138, v114, v115
	v_cvt_pk_bf16_f32 v139, v116, v117
	s_waitcnt vmcnt(0)
	ds_write_b128 v239, v[158:161] offset:27648
	v_mfma_f32_16x16x32_bf16 v[86:89], v[226:229], v[142:145], v[86:89]
	v_cvt_pk_bf16_f32 v140, v118, v119
	v_cvt_pk_bf16_f32 v141, v120, v121
	s_waitcnt lgkmcnt(0)
	s_barrier
; #define LAS __attribute__((address_space(3)))
; __device__ __forceinline__ f32x4 mfma16(bf16x8 a, bf16x8 b, f32x4 c) { return __builtin_amdgcn_mfma_f32_16x16x32_bf16(a, b, c, 0, 0, 0); }
; #define BAR_LDS() do { asm volatile("s_waitcnt lgkmcnt(0)" ::: "memory"); __builtin_amdgcn_s_barrier(); asm volatile("" ::: "memory"); } while (0)
; #define ATT_LOAD(tile) do { _Pragma("unroll") for (int i = 0; i < 2; ++i) { kr[i] = *(const u32x4*)(kg + (size_t)(64 * (tile) + 32 * i) * PP); vr[i] = *(const u32x4*)(vg + (size_t)(64 * (tile) + 32 * i) * PP); } } while (0)
; __device__ __forceinline__ void attn_step_fast(const LAS char* Kb, const LAS char* Vb, int lane, const bf16x8 (&qf)[2][2], const f32x4 negM, const bf16x8 onesf, f32x4 (&O)[2][8], f32x4 (&Oe)[2]) {
;     ...
;     bf16x8 va[8], vb[8];
; #pragma unroll
;     for (int nb = 0; nb < 8; ++nb) va[nb] = trfrag(Vb, APIT, 0, 16 * nb, lane);
; #pragma unroll
;     for (int nb = 0; nb < 8; ++nb) vb[nb] = trfrag(Vb, APIT, 32, 16 * nb, lane);
;     __builtin_amdgcn_sched_barrier(0);
;     Oe[0] = mfma16(onesf, p0[0], Oe[0]);
; #pragma unroll
;     for (int nb = 0; nb < 8; ++nb) O[0][nb] = mfma16(va[nb], p0[0], O[0][nb]);
;     Oe[0] = mfma16(onesf, p0[1], Oe[0]);
; #pragma unroll
;     for (int nb = 0; nb < 8; ++nb) O[0][nb] = mfma16(vb[nb], p0[1], O[0][nb]);
;     ATT_EXPPACK(s1, p1);
; #pragma unroll
;     for (int i = 0; i < 18; ++i) { __builtin_amdgcn_sched_group_barrier(0x008, 1, 0); __builtin_amdgcn_sched_group_barrier(0x002, 2, 0); }
;     __builtin_amdgcn_sched_barrier(0);
;     Oe[1] = mfma16(onesf, p1[0], Oe[1]);
; #pragma unroll
;     for (int nb = 0; nb < 8; ++nb) O[1][nb] = mfma16(va[nb], p1[0], O[1][nb]);
;     Oe[1] = mfma16(onesf, p1[1], Oe[1]);
; #pragma unroll
;     for (int nb = 0; nb < 8; ++nb) O[1][nb] = mfma16(vb[nb], p1[1], O[1][nb]);
; __device__ __forceinline__ void attn_item(LAS char* lds, bf16_t* proj, int bl, int h, int qb, float lam, float oscale, const float* gdh, float smax) {
;     ...
;     for (; t < NT - 2; ++t) {
;         ATT_LOAD(t + 1);
;         const LAS char* Kb = lds + (t & 1) * ABUF;
;     ...
;         attn_step_fast(Kb, Kb + ATILE, lane, qf, negM, onesf, O, Oe);
;     ...
;         { bf16x8 pq[2][2]; attn_qkexp(Kb, 64 * t, q0, wid, lane, g, qpos, qf, negM, pq); attn_pv(Kb + ATILE, lane, pq, onesf, O, Oe); }
;     ...
;         ATT_STORE((t + 1) & 1);
;         BAR_LDS();
	s_xor_b32 s49, s49, 0x9000
	s_xor_b32 s50, s50, 0x9000
	s_add_i32 s47, s47, -1
	s_cmp_lg_u32 s47, 0
	s_cbranch_scc1 .Lmy_attn_loop
	v_add_u32_e32 v181, s49, v230
	v_add_u32_e32 v205, s50, v231
	global_load_dwordx4 v[154:157], v240, s[4:5]
	global_load_dwordx4 v[158:161], v241, s[4:5]
	v_cvt_pk_bf16_f32 v134, v106, v107
	v_cvt_pk_bf16_f32 v135, v108, v109
	v_cvt_pk_bf16_f32 v136, v110, v111
	v_cvt_pk_bf16_f32 v137, v112, v113
	v_cvt_pk_bf16_f32 v142, v122, v123
	v_cvt_pk_bf16_f32 v143, v124, v125
	v_cvt_pk_bf16_f32 v144, v126, v127
	v_cvt_pk_bf16_f32 v145, v128, v129
	ds_read_b64_tr_b16 v[182:183], v205 offset:18432
	ds_read_b64_tr_b16 v[184:185], v205 offset:23040
	ds_read_b64_tr_b16 v[186:187], v205 offset:18464
	ds_read_b64_tr_b16 v[188:189], v205 offset:23072
	ds_read_b64_tr_b16 v[190:191], v205 offset:18496
	ds_read_b64_tr_b16 v[192:193], v205 offset:23104
	ds_read_b64_tr_b16 v[226:227], v205 offset:18528
	ds_read_b64_tr_b16 v[228:229], v205 offset:23136
	ds_read_b64_tr_b16 v[244:245], v205 offset:18560
	ds_read_b64_tr_b16 v[246:247], v205 offset:23168
	ds_read_b64_tr_b16 v[248:249], v205 offset:18592
	ds_read_b64_tr_b16 v[250:251], v205 offset:23200
	v_add_u32_e32 v238, s50, v179
	v_add_u32_e32 v239, s49, v179
	v_mfma_f32_16x16x32_bf16 v[94:97], v[74:77], v[130:133], v[94:97]
	v_mfma_f32_16x16x32_bf16 v[90:93], v[74:77], v[138:141], v[90:93]
	s_waitcnt lgkmcnt(10)
	v_mfma_f32_16x16x32_bf16 v[82:85], v[182:185], v[130:133], v[82:85]
	v_mfma_f32_16x16x32_bf16 v[78:81], v[182:185], v[138:141], v[78:81]
	ds_read_b64_tr_b16 v[182:183], v205 offset:18624
	ds_read_b64_tr_b16 v[184:185], v205 offset:23232
	s_waitcnt lgkmcnt(10)
	v_mfma_f32_16x16x32_bf16 v[70:73], v[186:189], v[130:133], v[70:73]
	v_mfma_f32_16x16x32_bf16 v[62:65], v[186:189], v[138:141], v[62:65]
	ds_read_b64_tr_b16 v[186:187], v205 offset:18656
	ds_read_b64_tr_b16 v[188:189], v205 offset:23264
	s_waitcnt lgkmcnt(10)
	v_mfma_f32_16x16x32_bf16 v[58:61], v[190:193], v[130:133], v[58:61]
	v_mfma_f32_16x16x32_bf16 v[54:57], v[190:193], v[138:141], v[54:57]
	ds_read_b64_tr_b16 v[190:191], v205 offset:27648
	ds_read_b64_tr_b16 v[192:193], v205 offset:32256
	s_waitcnt lgkmcnt(10)
	v_mfma_f32_16x16x32_bf16 v[46:49], v[226:229], v[130:133], v[46:49]
	v_mfma_f32_16x16x32_bf16 v[30:33], v[226:229], v[138:141], v[30:33]
	ds_read_b64_tr_b16 v[226:227], v205 offset:27680
	ds_read_b64_tr_b16 v[228:229], v205 offset:32288
	s_waitcnt lgkmcnt(10)
	v_mfma_f32_16x16x32_bf16 v[26:29], v[244:247], v[130:133], v[26:29]
	v_mfma_f32_16x16x32_bf16 v[22:25], v[244:247], v[138:141], v[22:25]
	ds_read_b64_tr_b16 v[244:245], v205 offset:27712
	ds_read_b64_tr_b16 v[246:247], v205 offset:32320
	s_waitcnt lgkmcnt(10)
	v_mfma_f32_16x16x32_bf16 v[18:21], v[248:251], v[130:133], v[18:21]
	v_mfma_f32_16x16x32_bf16 v[14:17], v[248:251], v[138:141], v[14:17]
	ds_read_b64_tr_b16 v[248:249], v205 offset:27744
	ds_read_b64_tr_b16 v[250:251], v205 offset:32352
	s_waitcnt lgkmcnt(10)
	v_mfma_f32_16x16x32_bf16 v[6:9], v[182:185], v[130:133], v[6:9]
	v_mfma_f32_16x16x32_bf16 v[10:13], v[182:185], v[138:141], v[10:13]
	ds_read_b64_tr_b16 v[182:183], v205 offset:27776
	ds_read_b64_tr_b16 v[184:185], v205 offset:32384
	s_waitcnt lgkmcnt(10)
	v_mfma_f32_16x16x32_bf16 v[66:69], v[186:189], v[130:133], v[66:69]
	v_mfma_f32_16x16x32_bf16 v[86:89], v[186:189], v[138:141], v[86:89]
	ds_read_b64_tr_b16 v[186:187], v205 offset:27808
	ds_read_b64_tr_b16 v[188:189], v205 offset:32416
	v_mfma_f32_16x16x32_bf16 v[94:97], v[74:77], v[134:137], v[94:97]
	v_mfma_f32_16x16x32_bf16 v[90:93], v[74:77], v[142:145], v[90:93]
	s_waitcnt lgkmcnt(10)
	v_mfma_f32_16x16x32_bf16 v[82:85], v[190:193], v[134:137], v[82:85]
	v_mfma_f32_16x16x32_bf16 v[78:81], v[190:193], v[142:145], v[78:81]
	ds_read_b64_tr_b16 v[190:191], v205 offset:27840
	ds_read_b64_tr_b16 v[192:193], v205 offset:32448
	s_waitcnt lgkmcnt(10)
	v_mfma_f32_16x16x32_bf16 v[70:73], v[226:229], v[134:137], v[70:73]
	v_mfma_f32_16x16x32_bf16 v[62:65], v[226:229], v[142:145], v[62:65]
	ds_read_b64_tr_b16 v[226:227], v205 offset:27872
	ds_read_b64_tr_b16 v[228:229], v205 offset:32480
	s_waitcnt lgkmcnt(10)
	v_mfma_f32_16x16x32_bf16 v[58:61], v[244:247], v[134:137], v[58:61]
	v_mfma_f32_16x16x32_bf16 v[54:57], v[244:247], v[142:145], v[54:57]
	s_waitcnt lgkmcnt(8)
	v_mfma_f32_16x16x32_bf16 v[46:49], v[248:251], v[134:137], v[46:49]
	v_mfma_f32_16x16x32_bf16 v[30:33], v[248:251], v[142:145], v[30:33]
	s_waitcnt lgkmcnt(6)
	v_mfma_f32_16x16x32_bf16 v[26:29], v[182:185], v[134:137], v[26:29]
	s_waitcnt vmcnt(1)
	ds_write_b128 v239, v[154:157] offset:18432
	v_mfma_f32_16x16x32_bf16 v[22:25], v[182:185], v[142:145], v[22:25]
	s_waitcnt lgkmcnt(5)
	v_mfma_f32_16x16x32_bf16 v[18:21], v[186:189], v[134:137], v[18:21]
	s_waitcnt vmcnt(0)
	ds_write_b128 v239, v[158:161] offset:27648
	v_mfma_f32_16x16x32_bf16 v[14:17], v[186:189], v[142:145], v[14:17]
	s_waitcnt lgkmcnt(4)
	v_mfma_f32_16x16x32_bf16 v[6:9], v[190:193], v[134:137], v[6:9]
	v_mfma_f32_16x16x32_bf16 v[10:13], v[190:193], v[142:145], v[10:13]
	s_waitcnt lgkmcnt(2)
	v_mfma_f32_16x16x32_bf16 v[66:69], v[226:229], v[134:137], v[66:69]
	v_mfma_f32_16x16x32_bf16 v[86:89], v[226:229], v[142:145], v[86:89]
	s_waitcnt lgkmcnt(0)
	s_barrier
